# v20 + FF-IN first-iteration SP2 wait counts the epilogue's stores (vmcnt 16) + MoBA gathered-Q copy vmcnt(4)
# speedup vs baseline: 1.0026x; 1.0026x over previous
; #define PG8_STAGE(bufoff, gbase, voff) do { _Pragma("unroll") for (int _i = 0; _i < 2; ++_i) \
;         __builtin_amdgcn_global_load_lds((const unsigned*)((const char*)(gbase) + (voff)[_i]), (PG8_LAS unsigned*)(lds + (bufoff) + ldsw + _i * 8192), 16, 0, 0); } while (0)
; #define PG8_LDA(dst, b, h) do { _Pragma("unroll") for (int m = 0; m < 4; ++m) _Pragma("unroll") for (int k = 0; k < 2; ++k) dst[m][k] = *(const PG8_LAS bf16x8*)(lds + PG8_SA(b, h) + aoff + m * 2048 + k * 1024); } while (0)
; #define PG8_MMA(ai, bj, At, Bt) do { __builtin_amdgcn_s_setprio(1); _Pragma("unroll") for (int m = 0; m < 4; ++m) _Pragma("unroll") for (int n = 0; n < 2; ++n) _Pragma("unroll") for (int k = 0; k < 2; ++k) \
;         acc[ai][bj][m][n] = __builtin_amdgcn_mfma_f32_16x16x32_bf16(Bt[n][k], At[m][k], acc[ai][bj][m][n], 0, 0, 0); __builtin_amdgcn_s_setprio(0); } while (0)
; #define PG8_WAIT_V(n) asm volatile("s_waitcnt vmcnt(" #n ")" ::: "memory")
; #define PG8_WAIT_L(n) asm volatile("s_waitcnt lgkmcnt(" #n ")" ::: "memory")
; #define PG8_BAR __builtin_amdgcn_s_barrier()
; #define PG8_SCHED __builtin_amdgcn_sched_barrier(0)
; template <class Epi, class Sched, bool ALIGN_EPI = false, bool SP2 = false>
; __device__ __forceinline__ void gemm_phase(PG8_LAS unsigned char* lds, const Gemm g, const Sched& S, const Epi& E) {
;     ...
;             PG8_WAIT_V(8); PG8_WAIT_L(0); PG8_BAR; PG8_MMA(0, 0, At, B0); PG8_MMA(0, 1, At, B1); PG8_BAR; PG8_SCHED;
;             PG8_LDA(At, 0, 1); PG8_STAGE(PG8_SB(0, 0), b2, voffB); PG8_STAGE(PG8_SB(0, 1), b2 + hstep, voffB); PG8_STAGE(PG8_SA(0, 0), a2, voffA);
;             PG8_WAIT_V(8); PG8_WAIT_L(0); PG8_BAR; PG8_MMA(1, 0, At, B0); PG8_MMA(1, 1, At, B1); PG8_BAR; PG8_SCHED;
.Lffin_noz:
	s_waitcnt vmcnt(8)
	s_waitcnt lgkmcnt(0)
	s_barrier
	s_setprio 1
	s_waitcnt lgkmcnt(0)
	v_mfma_f32_16x16x32_bf16 v[158:161], v[106:109], v[162:165], v[158:161]
	v_mfma_f32_16x16x32_bf16 v[154:157], v[114:117], v[162:165], v[154:157]
	v_mfma_f32_16x16x32_bf16 v[142:145], v[106:109], v[170:173], v[142:145]
	v_mfma_f32_16x16x32_bf16 v[138:141], v[114:117], v[170:173], v[138:141]
	v_mfma_f32_16x16x32_bf16 v[94:97], v[106:109], v[196:199], v[94:97]
	v_mfma_f32_16x16x32_bf16 v[90:93], v[114:117], v[196:199], v[90:93]
	v_mfma_f32_16x16x32_bf16 v[78:81], v[106:109], v[204:207], v[78:81]
	v_mfma_f32_16x16x32_bf16 v[74:77], v[114:117], v[204:207], v[74:77]
	v_mfma_f32_16x16x32_bf16 v[158:161], v[110:113], v[166:169], v[158:161]
	v_mfma_f32_16x16x32_bf16 v[154:157], v[118:121], v[166:169], v[154:157]
	v_mfma_f32_16x16x32_bf16 v[142:145], v[110:113], v[192:195], v[142:145]
	v_mfma_f32_16x16x32_bf16 v[138:141], v[118:121], v[192:195], v[138:141]
	v_mfma_f32_16x16x32_bf16 v[94:97], v[110:113], v[200:203], v[94:97]
	v_mfma_f32_16x16x32_bf16 v[90:93], v[118:121], v[200:203], v[90:93]
	v_mfma_f32_16x16x32_bf16 v[78:81], v[110:113], v[208:211], v[78:81]
	v_mfma_f32_16x16x32_bf16 v[74:77], v[118:121], v[208:211], v[74:77]
	s_setprio 0
	s_setprio 1
	v_mfma_f32_16x16x32_bf16 v[150:153], v[122:125], v[162:165], v[150:153]
	v_mfma_f32_16x16x32_bf16 v[146:149], v[130:133], v[162:165], v[146:149]
	v_mfma_f32_16x16x32_bf16 v[102:105], v[122:125], v[170:173], v[102:105]
	v_mfma_f32_16x16x32_bf16 v[98:101], v[130:133], v[170:173], v[98:101]
	v_mfma_f32_16x16x32_bf16 v[86:89], v[122:125], v[196:199], v[86:89]
	v_mfma_f32_16x16x32_bf16 v[82:85], v[130:133], v[196:199], v[82:85]
	v_mfma_f32_16x16x32_bf16 v[70:73], v[122:125], v[204:207], v[70:73]
	v_mfma_f32_16x16x32_bf16 v[66:69], v[130:133], v[204:207], v[66:69]
	v_mfma_f32_16x16x32_bf16 v[150:153], v[126:129], v[166:169], v[150:153]
	v_mfma_f32_16x16x32_bf16 v[146:149], v[134:137], v[166:169], v[146:149]
	v_mfma_f32_16x16x32_bf16 v[102:105], v[126:129], v[192:195], v[102:105]
	v_mfma_f32_16x16x32_bf16 v[98:101], v[134:137], v[192:195], v[98:101]
	v_mfma_f32_16x16x32_bf16 v[86:89], v[126:129], v[200:203], v[86:89]
	v_mfma_f32_16x16x32_bf16 v[82:85], v[134:137], v[200:203], v[82:85]
	v_mfma_f32_16x16x32_bf16 v[70:73], v[126:129], v[208:211], v[70:73]
	v_mfma_f32_16x16x32_bf16 v[66:69], v[134:137], v[208:211], v[66:69]
	s_setprio 0
	s_barrier
	s_add_i32 s69, s69, s52
	v_lshl_add_u64 v[212:213], s[44:45], 0, v[184:185]
	s_mov_b32 m0, s69
	ds_read_b128 v[162:165], v230 offset:16384
	ds_read_b128 v[166:169], v230 offset:17408
	ds_read_b128 v[170:173], v230 offset:18432
	ds_read_b128 v[192:195], v230 offset:19456
	ds_read_b128 v[196:199], v230 offset:20480
	ds_read_b128 v[200:203], v230 offset:21504
	ds_read_b128 v[204:207], v230 offset:22528
	ds_read_b128 v[208:211], v230 offset:23552
	global_load_lds_dwordx4 v[212:213], off
	s_add_i32 m0, s69, 0x2000
	s_add_u32 s70, s44, 0x40000
	v_lshl_add_u64 v[214:215], s[44:45], 0, v[180:181]
	s_addc_u32 s71, s45, 0
	s_add_i32 s69, s72, s52
	global_load_lds_dwordx4 v[214:215], off
	v_lshl_add_u64 v[216:217], s[70:71], 0, v[184:185]
	s_mov_b32 m0, s69
	v_lshl_add_u64 v[218:219], s[46:47], 0, v[182:183]
	global_load_lds_dwordx4 v[216:217], off
	v_lshl_add_u64 v[216:217], s[70:71], 0, v[180:181]
	s_add_i32 m0, s69, 0x2000
	s_nop 0
	global_load_lds_dwordx4 v[216:217], off
	v_lshl_add_u64 v[216:217], s[46:47], 0, v[186:187]
	s_mov_b32 m0, s53
	s_nop 0
	global_load_lds_dwordx4 v[216:217], off
	s_mov_b32 m0, s54
	s_nop 0
	global_load_lds_dwordx4 v[218:219], off
	s_cmp_lg_u32 s68, -2
	s_cbranch_scc1 .Lffin_w8
	s_cmp_lt_u32 s57, 2
	s_cbranch_scc1 .Lffin_w8
	s_waitcnt vmcnt(16)
	s_branch .Lffin_wd

; #define PG8_STAGE(bufoff, gbase, voff) do { _Pragma("unroll") for (int _i = 0; _i < 2; ++_i) \
;         __builtin_amdgcn_global_load_lds((const unsigned*)((const char*)(gbase) + (voff)[_i]), (PG8_LAS unsigned*)(lds + (bufoff) + ldsw + _i * 8192), 16, 0, 0); } while (0)
; #define PG8_LDA(dst, b, h) do { _Pragma("unroll") for (int m = 0; m < 4; ++m) _Pragma("unroll") for (int k = 0; k < 2; ++k) dst[m][k] = *(const PG8_LAS bf16x8*)(lds + PG8_SA(b, h) + aoff + m * 2048 + k * 1024); } while (0)
; #define PG8_LDB(dst, b, h) do { _Pragma("unroll") for (int n = 0; n < 2; ++n) _Pragma("unroll") for (int k = 0; k < 2; ++k) dst[n][k] = *(const PG8_LAS bf16x8*)(lds + PG8_SB(b, h) + boff + n * 2048 + k * 1024); } while (0)
; #define PG8_MMA(ai, bj, At, Bt) do { __builtin_amdgcn_s_setprio(1); _Pragma("unroll") for (int m = 0; m < 4; ++m) _Pragma("unroll") for (int n = 0; n < 2; ++n) _Pragma("unroll") for (int k = 0; k < 2; ++k) \
;         acc[ai][bj][m][n] = __builtin_amdgcn_mfma_f32_16x16x32_bf16(Bt[n][k], At[m][k], acc[ai][bj][m][n], 0, 0, 0); __builtin_amdgcn_s_setprio(0); } while (0)
; #define PG8_WAIT_V(n) asm volatile("s_waitcnt vmcnt(" #n ")" ::: "memory")
; #define PG8_WAIT_L(n) asm volatile("s_waitcnt lgkmcnt(" #n ")" ::: "memory")
; #define PG8_BAR __builtin_amdgcn_s_barrier()
; #define PG8_SCHED __builtin_amdgcn_sched_barrier(0)
; template <class Epi, class Sched, bool ALIGN_EPI = false, bool SP2 = false>
; __device__ __forceinline__ void gemm_phase(PG8_LAS unsigned char* lds, const Gemm g, const Sched& S, const Epi& E) {
;     ...
;             PG8_WAIT_V(8); PG8_WAIT_L(0); PG8_BAR; PG8_MMA(1, 0, At, B0); PG8_MMA(1, 1, At, B1); PG8_BAR; PG8_SCHED;
;             PG8_LDB(B0, 1, 0); PG8_LDB(B1, 1, 1); PG8_SCHED; PG8_LDA(At, 1, 0); PG8_STAGE(PG8_SA(0, 1), a2 + hstep, voffA);
;             PG8_WAIT_V(8); PG8_WAIT_L(0); PG8_BAR; PG8_MMA(0, 0, At, B0); PG8_MMA(0, 1, At, B1); PG8_BAR; PG8_SCHED;
.Lffin_wd:
	s_waitcnt lgkmcnt(0)
	s_barrier
	s_setprio 1
	s_waitcnt lgkmcnt(0)
	v_mfma_f32_16x16x32_bf16 v[62:65], v[106:109], v[162:165], v[62:65]
	v_mfma_f32_16x16x32_bf16 v[58:61], v[114:117], v[162:165], v[58:61]
	v_mfma_f32_16x16x32_bf16 v[46:49], v[106:109], v[170:173], v[46:49]
	v_mfma_f32_16x16x32_bf16 v[42:45], v[114:117], v[170:173], v[42:45]
	v_mfma_f32_16x16x32_bf16 v[30:33], v[106:109], v[196:199], v[30:33]
	v_mfma_f32_16x16x32_bf16 v[26:29], v[114:117], v[196:199], v[26:29]
	v_mfma_f32_16x16x32_bf16 v[14:17], v[106:109], v[204:207], v[14:17]
	v_mfma_f32_16x16x32_bf16 v[10:13], v[114:117], v[204:207], v[10:13]
	v_mfma_f32_16x16x32_bf16 v[62:65], v[110:113], v[166:169], v[62:65]
	v_mfma_f32_16x16x32_bf16 v[58:61], v[118:121], v[166:169], v[58:61]
	v_mfma_f32_16x16x32_bf16 v[46:49], v[110:113], v[192:195], v[46:49]
	v_mfma_f32_16x16x32_bf16 v[42:45], v[118:121], v[192:195], v[42:45]
	v_mfma_f32_16x16x32_bf16 v[30:33], v[110:113], v[200:203], v[30:33]
	v_mfma_f32_16x16x32_bf16 v[26:29], v[118:121], v[200:203], v[26:29]
	v_mfma_f32_16x16x32_bf16 v[14:17], v[110:113], v[208:211], v[14:17]
	v_mfma_f32_16x16x32_bf16 v[10:13], v[118:121], v[208:211], v[10:13]
	s_setprio 0
	s_setprio 1
	v_mfma_f32_16x16x32_bf16 v[54:57], v[122:125], v[162:165], v[54:57]
	v_mfma_f32_16x16x32_bf16 v[50:53], v[130:133], v[162:165], v[50:53]
	v_mfma_f32_16x16x32_bf16 v[38:41], v[122:125], v[170:173], v[38:41]
	v_mfma_f32_16x16x32_bf16 v[34:37], v[130:133], v[170:173], v[34:37]
	v_mfma_f32_16x16x32_bf16 v[22:25], v[122:125], v[196:199], v[22:25]
	v_mfma_f32_16x16x32_bf16 v[18:21], v[130:133], v[196:199], v[18:21]
	v_mfma_f32_16x16x32_bf16 v[6:9], v[122:125], v[204:207], v[6:9]
	v_mfma_f32_16x16x32_bf16 v[2:5], v[130:133], v[204:207], v[2:5]
	v_mfma_f32_16x16x32_bf16 v[54:57], v[126:129], v[166:169], v[54:57]
	v_mfma_f32_16x16x32_bf16 v[50:53], v[134:137], v[166:169], v[50:53]
	v_mfma_f32_16x16x32_bf16 v[38:41], v[126:129], v[192:195], v[38:41]
	v_mfma_f32_16x16x32_bf16 v[34:37], v[134:137], v[192:195], v[34:37]
	v_mfma_f32_16x16x32_bf16 v[22:25], v[126:129], v[200:203], v[22:25]
	v_mfma_f32_16x16x32_bf16 v[18:21], v[134:137], v[200:203], v[18:21]
	v_mfma_f32_16x16x32_bf16 v[6:9], v[126:129], v[208:211], v[6:9]
	v_mfma_f32_16x16x32_bf16 v[2:5], v[134:137], v[208:211], v[2:5]
	s_setprio 0
	s_barrier
	s_add_i32 s69, 0, 0x18000
	s_add_i32 s70, 0, 0x1c000
	v_add_u32_e32 v118, s69, v229
	v_add_u32_e32 v134, s70, v229
	ds_read_b128 v[106:109], v118
	ds_read_b128 v[110:113], v118 offset:1024
	ds_read_b128 v[114:117], v118 offset:2048
	ds_read_b128 v[118:121], v118 offset:3072
	ds_read_b128 v[122:125], v134
	ds_read_b128 v[126:129], v134 offset:1024
	ds_read_b128 v[130:133], v134 offset:2048
	ds_read_b128 v[134:137], v134 offset:3072
	s_add_u32 s46, s46, 0x40000
	s_addc_u32 s47, s47, 0
	s_mov_b32 m0, s55
	v_lshl_add_u64 v[220:221], s[46:47], 0, v[186:187]
	ds_read_b128 v[162:165], v230 offset:32768
	ds_read_b128 v[166:169], v230 offset:33792
	ds_read_b128 v[170:173], v230 offset:34816
	ds_read_b128 v[192:195], v230 offset:35840
	ds_read_b128 v[196:199], v230 offset:36864
	ds_read_b128 v[200:203], v230 offset:37888
	ds_read_b128 v[204:207], v230 offset:38912
	ds_read_b128 v[208:211], v230 offset:39936
	global_load_lds_dwordx4 v[220:221], off
	v_lshl_add_u64 v[220:221], s[46:47], 0, v[182:183]
	s_mov_b32 m0, s56
	s_nop 0
	global_load_lds_dwordx4 v[220:221], off
	s_waitcnt vmcnt(8)
	s_waitcnt lgkmcnt(0)
	s_barrier
	s_setprio 1
	s_waitcnt lgkmcnt(0)
	v_mfma_f32_16x16x32_bf16 v[158:161], v[106:109], v[162:165], v[158:161]
	v_mfma_f32_16x16x32_bf16 v[154:157], v[114:117], v[162:165], v[154:157]
	v_mfma_f32_16x16x32_bf16 v[142:145], v[106:109], v[170:173], v[142:145]
	v_mfma_f32_16x16x32_bf16 v[138:141], v[114:117], v[170:173], v[138:141]
	v_mfma_f32_16x16x32_bf16 v[94:97], v[106:109], v[196:199], v[94:97]
	v_mfma_f32_16x16x32_bf16 v[90:93], v[114:117], v[196:199], v[90:93]
	v_mfma_f32_16x16x32_bf16 v[78:81], v[106:109], v[204:207], v[78:81]
	v_mfma_f32_16x16x32_bf16 v[74:77], v[114:117], v[204:207], v[74:77]
	v_mfma_f32_16x16x32_bf16 v[158:161], v[110:113], v[166:169], v[158:161]
	v_mfma_f32_16x16x32_bf16 v[154:157], v[118:121], v[166:169], v[154:157]
	v_mfma_f32_16x16x32_bf16 v[142:145], v[110:113], v[192:195], v[142:145]
	v_mfma_f32_16x16x32_bf16 v[138:141], v[118:121], v[192:195], v[138:141]
	v_mfma_f32_16x16x32_bf16 v[94:97], v[110:113], v[200:203], v[94:97]
	v_mfma_f32_16x16x32_bf16 v[90:93], v[118:121], v[200:203], v[90:93]
	v_mfma_f32_16x16x32_bf16 v[78:81], v[110:113], v[208:211], v[78:81]
	v_mfma_f32_16x16x32_bf16 v[74:77], v[118:121], v[208:211], v[74:77]
	s_setprio 0
	s_setprio 1
	v_mfma_f32_16x16x32_bf16 v[150:153], v[122:125], v[162:165], v[150:153]
	v_mfma_f32_16x16x32_bf16 v[146:149], v[130:133], v[162:165], v[146:149]
	v_mfma_f32_16x16x32_bf16 v[102:105], v[122:125], v[170:173], v[102:105]
	v_mfma_f32_16x16x32_bf16 v[98:101], v[130:133], v[170:173], v[98:101]
	v_mfma_f32_16x16x32_bf16 v[86:89], v[122:125], v[196:199], v[86:89]
	v_mfma_f32_16x16x32_bf16 v[82:85], v[130:133], v[196:199], v[82:85]
	v_mfma_f32_16x16x32_bf16 v[70:73], v[122:125], v[204:207], v[70:73]
	v_mfma_f32_16x16x32_bf16 v[66:69], v[130:133], v[204:207], v[66:69]
	v_mfma_f32_16x16x32_bf16 v[150:153], v[126:129], v[166:169], v[150:153]
	v_mfma_f32_16x16x32_bf16 v[146:149], v[134:137], v[166:169], v[146:149]
	v_mfma_f32_16x16x32_bf16 v[102:105], v[126:129], v[192:195], v[102:105]
	v_mfma_f32_16x16x32_bf16 v[98:101], v[134:137], v[192:195], v[98:101]
	v_mfma_f32_16x16x32_bf16 v[86:89], v[126:129], v[200:203], v[86:89]
	v_mfma_f32_16x16x32_bf16 v[82:85], v[134:137], v[200:203], v[82:85]
	v_mfma_f32_16x16x32_bf16 v[70:73], v[126:129], v[208:211], v[70:73]
	v_mfma_f32_16x16x32_bf16 v[66:69], v[134:137], v[208:211], v[66:69]
	s_setprio 0
	s_barrier
; #define PG8_STAGE(bufoff, gbase, voff) do { _Pragma("unroll") for (int _i = 0; _i < 2; ++_i) \
;         __builtin_amdgcn_global_load_lds((const unsigned*)((const char*)(gbase) + (voff)[_i]), (PG8_LAS unsigned*)(lds + (bufoff) + ldsw + _i * 8192), 16, 0, 0); } while (0)
; #define PG8_LDA(dst, b, h) do { _Pragma("unroll") for (int m = 0; m < 4; ++m) _Pragma("unroll") for (int k = 0; k < 2; ++k) dst[m][k] = *(const PG8_LAS bf16x8*)(lds + PG8_SA(b, h) + aoff + m * 2048 + k * 1024); } while (0)
; #define PG8_MMA(ai, bj, At, Bt) do { __builtin_amdgcn_s_setprio(1); _Pragma("unroll") for (int m = 0; m < 4; ++m) _Pragma("unroll") for (int n = 0; n < 2; ++n) _Pragma("unroll") for (int k = 0; k < 2; ++k) \
;         acc[ai][bj][m][n] = __builtin_amdgcn_mfma_f32_16x16x32_bf16(Bt[n][k], At[m][k], acc[ai][bj][m][n], 0, 0, 0); __builtin_amdgcn_s_setprio(0); } while (0)
; #define PG8_WAIT_V(n) asm volatile("s_waitcnt vmcnt(" #n ")" ::: "memory")
; #define PG8_WAIT_L(n) asm volatile("s_waitcnt lgkmcnt(" #n ")" ::: "memory")
; #define PG8_BAR __builtin_amdgcn_s_barrier()
; #define PG8_SCHED __builtin_amdgcn_sched_barrier(0)
; template <class Epi, class Sched, bool ALIGN_EPI = false, bool SP2 = false>
; __device__ __forceinline__ void gemm_phase(PG8_LAS unsigned char* lds, const Gemm g, const Sched& S, const Epi& E) {
;     ...
;             PG8_LDA(At, 1, 1); PG8_STAGE(PG8_SB(1, 0), b3, voffB); PG8_STAGE(PG8_SB(1, 1), b3 + hstep, voffB); PG8_STAGE(PG8_SA(1, 0), a3, voffA);
;             PG8_WAIT_V(8); PG8_WAIT_L(0); PG8_BAR; PG8_MMA(1, 0, At, B0); PG8_MMA(1, 1, At, B1); PG8_BAR; PG8_SCHED;
;     ...
;         if constexpr (ALIGN_EPI) { if (wr == 0) PG8_BAR; }
	s_add_i32 s46, s69, s52
	v_lshl_add_u64 v[212:213], v[212:213], 0, s[96:97]
	s_mov_b32 m0, s46
	ds_read_b128 v[162:165], v230 offset:49152
	ds_read_b128 v[166:169], v230 offset:50176
	ds_read_b128 v[170:173], v230 offset:51200
	ds_read_b128 v[192:195], v230 offset:52224
	ds_read_b128 v[196:199], v230 offset:53248
	ds_read_b128 v[200:203], v230 offset:54272
	ds_read_b128 v[204:207], v230 offset:55296
	ds_read_b128 v[208:211], v230 offset:56320
	global_load_lds_dwordx4 v[212:213], off
	s_add_i32 m0, s46, 0x2000
	s_add_u32 s44, s44, 0x40080
	v_lshl_add_u64 v[212:213], v[214:215], 0, s[96:97]
	s_addc_u32 s45, s45, 0
	s_add_i32 s46, s70, s52
	global_load_lds_dwordx4 v[212:213], off
	v_lshl_add_u64 v[212:213], s[44:45], 0, v[184:185]
	s_mov_b32 m0, s46
	s_nop 0
	global_load_lds_dwordx4 v[212:213], off
	v_lshl_add_u64 v[212:213], s[44:45], 0, v[180:181]
	s_add_i32 m0, s46, 0x2000
	s_nop 0
	global_load_lds_dwordx4 v[212:213], off
	v_lshl_add_u64 v[212:213], v[216:217], 0, s[96:97]
	s_mov_b32 m0, s60
	s_nop 0
	global_load_lds_dwordx4 v[212:213], off
	v_lshl_add_u64 v[212:213], v[218:219], 0, s[96:97]
	s_mov_b32 m0, s61
	s_nop 0
	global_load_lds_dwordx4 v[212:213], off
	s_waitcnt vmcnt(8)
	s_waitcnt lgkmcnt(0)
	s_barrier
	s_setprio 1
	s_waitcnt lgkmcnt(0)
	v_mfma_f32_16x16x32_bf16 v[62:65], v[106:109], v[162:165], v[62:65]
	v_mfma_f32_16x16x32_bf16 v[58:61], v[114:117], v[162:165], v[58:61]
	v_mfma_f32_16x16x32_bf16 v[46:49], v[106:109], v[170:173], v[46:49]
	v_mfma_f32_16x16x32_bf16 v[42:45], v[114:117], v[170:173], v[42:45]
	v_mfma_f32_16x16x32_bf16 v[30:33], v[106:109], v[196:199], v[30:33]
	v_mfma_f32_16x16x32_bf16 v[26:29], v[114:117], v[196:199], v[26:29]
	v_mfma_f32_16x16x32_bf16 v[14:17], v[106:109], v[204:207], v[14:17]
	v_mfma_f32_16x16x32_bf16 v[10:13], v[114:117], v[204:207], v[10:13]
	v_mfma_f32_16x16x32_bf16 v[62:65], v[110:113], v[166:169], v[62:65]
	v_mfma_f32_16x16x32_bf16 v[58:61], v[118:121], v[166:169], v[58:61]
	v_mfma_f32_16x16x32_bf16 v[46:49], v[110:113], v[192:195], v[46:49]
	v_mfma_f32_16x16x32_bf16 v[42:45], v[118:121], v[192:195], v[42:45]
	v_mfma_f32_16x16x32_bf16 v[30:33], v[110:113], v[200:203], v[30:33]
	v_mfma_f32_16x16x32_bf16 v[26:29], v[118:121], v[200:203], v[26:29]
	v_mfma_f32_16x16x32_bf16 v[14:17], v[110:113], v[208:211], v[14:17]
	v_mfma_f32_16x16x32_bf16 v[10:13], v[118:121], v[208:211], v[10:13]
	s_setprio 0
	s_setprio 1
	v_mfma_f32_16x16x32_bf16 v[54:57], v[122:125], v[162:165], v[54:57]
	v_mfma_f32_16x16x32_bf16 v[50:53], v[130:133], v[162:165], v[50:53]
	v_mfma_f32_16x16x32_bf16 v[38:41], v[122:125], v[170:173], v[38:41]
	v_mfma_f32_16x16x32_bf16 v[34:37], v[130:133], v[170:173], v[34:37]
	v_mfma_f32_16x16x32_bf16 v[22:25], v[122:125], v[196:199], v[22:25]
	v_mfma_f32_16x16x32_bf16 v[18:21], v[130:133], v[196:199], v[18:21]
	v_mfma_f32_16x16x32_bf16 v[6:9], v[122:125], v[204:207], v[6:9]
	v_mfma_f32_16x16x32_bf16 v[2:5], v[130:133], v[204:207], v[2:5]
	v_mfma_f32_16x16x32_bf16 v[54:57], v[126:129], v[166:169], v[54:57]
	v_mfma_f32_16x16x32_bf16 v[50:53], v[134:137], v[166:169], v[50:53]
	v_mfma_f32_16x16x32_bf16 v[38:41], v[126:129], v[192:195], v[38:41]
	v_mfma_f32_16x16x32_bf16 v[34:37], v[134:137], v[192:195], v[34:37]
	v_mfma_f32_16x16x32_bf16 v[22:25], v[126:129], v[200:203], v[22:25]
	v_mfma_f32_16x16x32_bf16 v[18:21], v[134:137], v[200:203], v[18:21]
	v_mfma_f32_16x16x32_bf16 v[6:9], v[126:129], v[208:211], v[6:9]
	v_mfma_f32_16x16x32_bf16 v[2:5], v[134:137], v[208:211], v[2:5]
	s_setprio 0
	s_barrier
	s_add_i32 s68, s68, 2
	s_add_u32 s8, s8, 0x100
	s_addc_u32 s9, s9, 0
	s_add_u32 s66, s66, 0x100
	s_addc_u32 s67, s67, 0
	s_cmp_gt_u32 s68, 13
	s_cbranch_scc0 .LBB0_1247
	s_and_b64 vcc, exec, s[24:25]
	s_cbranch_vccz .LBB0_1250
	s_barrier
